# swa_build_bias at the start of each +1 phase: serialized table lookups (byte->word->LDS, 4-6 round trips) batched into two round trips
# speedup vs baseline: 1.0065x; 1.0000x over previous
; #define LAS __attribute__((address_space(3)))
; #define REPEAT(k) for (int rep_ = 0; rep_ < ((k) == REP_SEL ? REP_N : 1); ++rep_)
; __device__ __forceinline__ void swa_build_bias(CArgs& A, Frame& F) {
;     LAS float* bt = (LAS float*)(F.lds + SW_BT); const float* rel = A.in[15];
;     for (int i = F.tid; i < 16 * 132; i += NT) { const int h = i / 132, dist = i % 132; bt[i] = rel[RELB[dist] * 16 + h]; }
; }
; __global__ void __launch_bounds__(NT, 2) fwd(const Args args) {
;     ...
;         if (IN(pb + 1)) REPEAT(2) { PHASE_BEGIN
;             swa_build_bias(A, F); __syncthreads();
.LBB0_349:
	s_andn2_b64 vcc, exec, s[0:1]
	s_cbranch_vccnz .LBB0_876
	v_readlane_b32 s0, v254, 41
	s_mov_b32 s2, s0
	v_readlane_b32 s0, v253, 5
	v_readlane_b32 s1, v253, 6
	v_readlane_b32 s64, v253, 0
	v_writelane_b32 v254, s2, 43
	s_nop 1
	v_writelane_b32 v254, s3, 44
	v_writelane_b32 v254, s0, 45
	s_load_dwordx4 s[80:83], s[0:1], 0xe0
	s_nop 0
	v_writelane_b32 v254, s1, 46
	s_mov_b32 s0, s9
	s_nop 0
	v_mbcnt_lo_u32_b32 v0, -1, s0
	v_readlane_b32 s0, v253, 11
	v_mbcnt_hi_u32_b32 v102, -1, v0
	s_mov_b32 s1, s0
	s_lshl_b32 s8, s1, 6
	v_add_u32_e32 v100, s8, v102
	s_movk_i32 s0, 0x840
	v_writelane_b32 v254, s1, 47
	v_cmp_gt_i32_e32 vcc, s0, v100
	s_and_saveexec_b64 s[0:1], vcc
	s_cbranch_execz .LBB0_363
	v_readlane_b32 s2, v254, 45
	v_readlane_b32 s3, v254, 46
	s_load_dwordx2 s[2:3], s[2:3], 0x78
	s_getpc_b64 s[12:13]
	s_add_u32 s12, s12, _ZL4RELB@rel32@lo+4
	s_addc_u32 s13, s13, _ZL4RELB@rel32@hi+12
	s_mov_b32 s15, 0x3e0f83e1
	s_movk_i32 s14, 0x84
	s_movk_i32 s4, 0x840
	v_mov_b32_e32 v104, v100
	v_mul_hi_i32 v105, v104, s15
	v_lshrrev_b32_e32 v111, 31, v105
	v_ashrrev_i32_e32 v105, 5, v105
	v_add_u32_e32 v105, v105, v111
	v_mul_lo_u32 v111, v105, s14
	v_sub_u32_e32 v106, v104, v111
	v_ashrrev_i32_e32 v107, 31, v106
	v_lshl_add_u64 v[108:109], s[12:13], 0, v[106:107]
	global_load_ubyte v110, v[108:109], off
	v_add_u32_e32 v112, 0x200, v100
	v_mul_hi_i32 v113, v112, s15
	v_lshrrev_b32_e32 v119, 31, v113
	v_ashrrev_i32_e32 v113, 5, v113
	v_add_u32_e32 v113, v113, v119
	v_mul_lo_u32 v119, v113, s14
	v_sub_u32_e32 v114, v112, v119
	v_ashrrev_i32_e32 v115, 31, v114
	v_lshl_add_u64 v[116:117], s[12:13], 0, v[114:115]
	global_load_ubyte v118, v[116:117], off
	v_add_u32_e32 v120, 0x400, v100
	v_mul_hi_i32 v121, v120, s15
	v_lshrrev_b32_e32 v127, 31, v121
	v_ashrrev_i32_e32 v121, 5, v121
	v_add_u32_e32 v121, v121, v127
	v_mul_lo_u32 v127, v121, s14
	v_sub_u32_e32 v122, v120, v127
	v_ashrrev_i32_e32 v123, 31, v122
	v_lshl_add_u64 v[124:125], s[12:13], 0, v[122:123]
	global_load_ubyte v126, v[124:125], off
	v_add_u32_e32 v128, 0x600, v100
	v_mul_hi_i32 v129, v128, s15
	v_lshrrev_b32_e32 v135, 31, v129
	v_ashrrev_i32_e32 v129, 5, v129
	v_add_u32_e32 v129, v129, v135
	v_mul_lo_u32 v135, v129, s14
	v_sub_u32_e32 v130, v128, v135
	v_ashrrev_i32_e32 v131, 31, v130
	v_lshl_add_u64 v[132:133], s[12:13], 0, v[130:131]
	global_load_ubyte v134, v[132:133], off
	v_add_u32_e32 v136, 0x800, v100
	v_cmp_gt_u32_e32 vcc, s4, v136
	v_cndmask_b32_e32 v136, v100, v136, vcc
	v_mul_hi_i32 v137, v136, s15
	v_lshrrev_b32_e32 v143, 31, v137
	v_ashrrev_i32_e32 v137, 5, v137
	v_add_u32_e32 v137, v137, v143
	v_mul_lo_u32 v143, v137, s14
	v_sub_u32_e32 v138, v136, v143
	v_ashrrev_i32_e32 v139, 31, v138
	v_lshl_add_u64 v[140:141], s[12:13], 0, v[138:139]
	global_load_ubyte v142, v[140:141], off
	s_waitcnt vmcnt(0) lgkmcnt(0)
	v_lshl_add_u32 v106, v110, 4, v105
	v_ashrrev_i32_e32 v107, 31, v106
	v_lshl_add_u64 v[108:109], v[106:107], 2, s[2:3]
	global_load_dword v110, v[108:109], off
	v_lshl_add_u32 v114, v118, 4, v113
	v_ashrrev_i32_e32 v115, 31, v114
	v_lshl_add_u64 v[116:117], v[114:115], 2, s[2:3]
	global_load_dword v118, v[116:117], off
	v_lshl_add_u32 v122, v126, 4, v121
	v_ashrrev_i32_e32 v123, 31, v122
	v_lshl_add_u64 v[124:125], v[122:123], 2, s[2:3]
	global_load_dword v126, v[124:125], off
	v_lshl_add_u32 v130, v134, 4, v129
	v_ashrrev_i32_e32 v131, 31, v130
	v_lshl_add_u64 v[132:133], v[130:131], 2, s[2:3]
	global_load_dword v134, v[132:133], off
	v_lshl_add_u32 v138, v142, 4, v137
	v_ashrrev_i32_e32 v139, 31, v138
	v_lshl_add_u64 v[140:141], v[138:139], 2, s[2:3]
	global_load_dword v142, v[140:141], off
	s_mov_b32 s4, 0x12900
	v_lshl_add_u32 v111, v104, 2, s4
	v_lshl_add_u32 v119, v112, 2, s4
	v_lshl_add_u32 v127, v120, 2, s4
	v_lshl_add_u32 v135, v128, 2, s4
	v_lshl_add_u32 v143, v136, 2, s4
	s_waitcnt vmcnt(4)
	ds_write_b32 v111, v110
	s_waitcnt vmcnt(3)
	ds_write_b32 v119, v118
	s_waitcnt vmcnt(2)
	ds_write_b32 v127, v126
	s_waitcnt vmcnt(1)
	ds_write_b32 v135, v134
	s_waitcnt vmcnt(0)
	ds_write_b32 v143, v142
